# GQA static prio given to waves 0-3 instead of 4-7 (direction check, on top of v18)
# baseline (speedup 1.0000x reference)
.LBB0_508:
	s_xor_b64 s[42:43], s[0:1], -1
	v_readlane_b32 s0, v251, 49
	v_mov_b32_e32 v42, v198
	s_add_i32 s0, s2, s0
	s_ashr_i32 s0, s0, 5
	v_readfirstlane_b32 s11, v42
	v_readlane_b32 s1, v251, 55
	s_ashr_i32 s10, s11, 6
	s_cmp_lt_u32 s10, 4
	s_cbranch_scc0 .Lgqa_prio_skip
	s_setprio 1
